# small-block attention loops: the f32-cache prefetch path skips the compiler's full vmcnt drain at the phi-copy join, so the next tile's 8 loads fly under the tile's arithmetic as the source intends (c
# speedup vs baseline: 1.0067x; 1.0067x over previous
.LBB0_963:
	s_andn2_b64 vcc, exec, s[2:3]
	s_cbranch_vccnz .LBB0_965
	s_waitcnt vmcnt(3)
	v_mul_lo_u32 v4, s15, v0
	v_mul_lo_u32 v5, s14, v14
	v_mad_u64_u32 v[2:3], s[2:3], s14, v0, 0
	v_add3_u32 v3, v3, v5, v4
	v_lshlrev_b64 v[2:3], 2, v[2:3]
	v_lshl_add_u64 v[4:5], v[198:199], 0, v[2:3]
	global_load_dwordx4 v[146:149], v[4:5], off offset:16
	global_load_dwordx4 v[150:153], v[4:5], off
	v_lshl_add_u64 v[4:5], v[4:5], 0, s[16:17]
	v_lshl_add_u64 v[2:3], v[200:201], 0, v[2:3]
	global_load_dwordx4 v[154:157], v[4:5], off offset:16
	global_load_dwordx4 v[158:161], v[4:5], off
	global_load_dwordx4 v[162:165], v[2:3], off offset:16
	global_load_dwordx4 v[166:169], v[2:3], off
	v_lshl_add_u64 v[2:3], v[2:3], 0, s[16:17]
	global_load_dwordx4 v[182:185], v[2:3], off offset:16
	global_load_dwordx4 v[178:181], v[2:3], off
	v_mov_b64_e32 v[2:3], v[170:171]
	s_waitcnt vmcnt(10)
	v_mov_b64_e32 v[6:7], v[174:175]
	s_waitcnt vmcnt(9)
	v_mov_b64_e32 v[10:11], v[186:187]
	s_waitcnt vmcnt(8)
	v_mov_b64_e32 v[82:83], v[190:191]
	v_mov_b64_e32 v[4:5], v[172:173]
	v_mov_b64_e32 v[8:9], v[176:177]
	v_mov_b64_e32 v[12:13], v[188:189]
	v_mov_b64_e32 v[84:85], v[192:193]
	s_branch .Lsm_nodrain_3

.Lsm_nodrain_3:
	v_mov_b64_e32 v[192:193], v[84:85]
	v_mov_b64_e32 v[188:189], v[12:13]
	v_mov_b64_e32 v[176:177], v[8:9]
	v_mov_b64_e32 v[172:173], v[4:5]
	v_mov_b64_e32 v[190:191], v[82:83]
	v_mov_b64_e32 v[186:187], v[10:11]
	v_mov_b64_e32 v[174:175], v[6:7]
	v_mov_b64_e32 v[170:171], v[2:3]

.LBB0_2522:
	s_andn2_b64 vcc, exec, s[20:21]
	s_cbranch_vccnz .LBB0_2524
	s_waitcnt vmcnt(3)
	v_mad_i64_i32 v[2:3], s[20:21], s48, v0, 0
	v_lshlrev_b64 v[2:3], 2, v[2:3]
	v_lshl_add_u64 v[4:5], v[198:199], 0, v[2:3]
	global_load_dwordx4 v[146:149], v[4:5], off offset:16
	global_load_dwordx4 v[150:153], v[4:5], off
	v_lshl_add_u64 v[4:5], v[4:5], 0, s[40:41]
	v_lshl_add_u64 v[2:3], v[200:201], 0, v[2:3]
	global_load_dwordx4 v[154:157], v[4:5], off offset:16
	global_load_dwordx4 v[158:161], v[4:5], off
	global_load_dwordx4 v[162:165], v[2:3], off offset:16
	global_load_dwordx4 v[166:169], v[2:3], off
	v_lshl_add_u64 v[2:3], v[2:3], 0, s[40:41]
	global_load_dwordx4 v[182:185], v[2:3], off offset:16
	global_load_dwordx4 v[178:181], v[2:3], off
	v_mov_b64_e32 v[2:3], v[170:171]
	s_waitcnt vmcnt(10)
	v_mov_b64_e32 v[6:7], v[174:175]
	s_waitcnt vmcnt(9)
	v_mov_b64_e32 v[10:11], v[186:187]
	s_waitcnt vmcnt(8)
	v_mov_b64_e32 v[82:83], v[190:191]
	v_mov_b64_e32 v[4:5], v[172:173]
	v_mov_b64_e32 v[8:9], v[176:177]
	v_mov_b64_e32 v[12:13], v[188:189]
	v_mov_b64_e32 v[84:85], v[192:193]
	s_branch .Lsm_nodrain_2

.LBB0_5093:
	s_andn2_b64 vcc, exec, s[20:21]
	s_cbranch_vccnz .LBB0_5095
	s_waitcnt vmcnt(3)
	v_mad_i64_i32 v[2:3], s[20:21], s50, v0, 0
	v_lshlrev_b64 v[2:3], 2, v[2:3]
	v_lshl_add_u64 v[4:5], v[198:199], 0, v[2:3]
	global_load_dwordx4 v[146:149], v[4:5], off offset:16
	global_load_dwordx4 v[150:153], v[4:5], off
	v_lshl_add_u64 v[4:5], v[4:5], 0, s[42:43]
	v_lshl_add_u64 v[2:3], v[200:201], 0, v[2:3]
	global_load_dwordx4 v[154:157], v[4:5], off offset:16
	global_load_dwordx4 v[158:161], v[4:5], off
	global_load_dwordx4 v[162:165], v[2:3], off offset:16
	global_load_dwordx4 v[166:169], v[2:3], off
	v_lshl_add_u64 v[2:3], v[2:3], 0, s[42:43]
	global_load_dwordx4 v[182:185], v[2:3], off offset:16
	global_load_dwordx4 v[178:181], v[2:3], off
	v_mov_b64_e32 v[2:3], v[170:171]
	s_waitcnt vmcnt(10)
	v_mov_b64_e32 v[6:7], v[174:175]
	s_waitcnt vmcnt(9)
	v_mov_b64_e32 v[10:11], v[186:187]
	s_waitcnt vmcnt(8)
	v_mov_b64_e32 v[82:83], v[190:191]
	v_mov_b64_e32 v[4:5], v[172:173]
	v_mov_b64_e32 v[8:9], v[176:177]
	v_mov_b64_e32 v[12:13], v[188:189]
	v_mov_b64_e32 v[84:85], v[192:193]
	s_branch .Lsm_nodrain_1

.LBB0_6739:
	s_andn2_b64 vcc, exec, s[26:27]
	s_cbranch_vccnz .LBB0_6741
	s_waitcnt vmcnt(3)
	v_mul_lo_u32 v4, s57, v0
	v_mul_lo_u32 v5, s56, v14
	v_mad_u64_u32 v[2:3], s[26:27], s56, v0, 0
	v_add3_u32 v3, v3, v5, v4
	v_lshlrev_b64 v[2:3], 2, v[2:3]
	v_lshl_add_u64 v[4:5], v[198:199], 0, v[2:3]
	global_load_dwordx4 v[146:149], v[4:5], off offset:16
	global_load_dwordx4 v[150:153], v[4:5], off
	v_lshl_add_u64 v[4:5], v[4:5], 0, s[22:23]
	v_lshl_add_u64 v[2:3], v[200:201], 0, v[2:3]
	global_load_dwordx4 v[154:157], v[4:5], off offset:16
	global_load_dwordx4 v[158:161], v[4:5], off
	global_load_dwordx4 v[162:165], v[2:3], off offset:16
	global_load_dwordx4 v[166:169], v[2:3], off
	v_lshl_add_u64 v[2:3], v[2:3], 0, s[22:23]
	global_load_dwordx4 v[182:185], v[2:3], off offset:16
	global_load_dwordx4 v[178:181], v[2:3], off
	v_mov_b64_e32 v[2:3], v[170:171]
	s_waitcnt vmcnt(10)
	v_mov_b64_e32 v[6:7], v[174:175]
	s_waitcnt vmcnt(9)
	v_mov_b64_e32 v[10:11], v[186:187]
	s_waitcnt vmcnt(8)
	v_mov_b64_e32 v[82:83], v[190:191]
	v_mov_b64_e32 v[4:5], v[172:173]
	v_mov_b64_e32 v[8:9], v[176:177]
	v_mov_b64_e32 v[12:13], v[188:189]
	v_mov_b64_e32 v[84:85], v[192:193]
	s_branch .Lsm_nodrain_0
